# grid barrier: workgroups that are not their XCD's last arriver poll the cross-XCD release generation directly (one release hop less per barrier)
# speedup vs baseline: 1.0003x; 1.0003x over previous
; __device__ __forceinline__ unsigned xb_ld(unsigned* p)              { return __hip_atomic_load(p, __ATOMIC_RELAXED, __HIP_MEMORY_SCOPE_AGENT); }
; __device__ __forceinline__ unsigned xb_add(unsigned* p, unsigned v) { return __hip_atomic_fetch_add(p, v, __ATOMIC_RELAXED, __HIP_MEMORY_SCOPE_AGENT); }
; #define XB_SPIN(cond, bar) do { unsigned _sp = 0; while (cond) { __builtin_amdgcn_s_sleep(1); \
;     if ((++_sp & 255u) == 0u) { if (xb_ld(&(bar)[XB_TMO])) break; if (_sp > XB_SPIN_CAP) { atomicAdd(&(bar)[XB_TMO], 1u); break; } } } } while (0)
; __device__ __forceinline__ void xcd_barrier(const XcdBarrier& b) {
;     ...
;         const unsigned old = xb_add(&bar[XB_XSUB(b.x)], 1u);
;         const unsigned gen = old / nloc;
;         if (old + 1u == (gen + 1u) * nloc) {
;             __builtin_amdgcn_fence(__ATOMIC_RELEASE, "agent");
;             asm volatile("s_waitcnt vmcnt(0)" ::: "memory");
;             const unsigned og = xb_add(&bar[XB_TOP], 1u);
;             const unsigned tg = og / nx;
;             if (og + 1u == (tg + 1u) * nx) xb_add(&bar[XB_TOPGEN], 1u);
;             else XB_SPIN(xb_ld(&bar[XB_TOPGEN]) == tg, bar);
;             __builtin_amdgcn_fence(__ATOMIC_ACQUIRE, "agent");
;             xb_add(&bar[XB_XGEN(b.x)], 1u);
;             asm volatile("s_waitcnt vmcnt(0)" ::: "memory");
;         } else {
;             XB_SPIN(xb_ld(&bar[XB_XGEN(b.x)]) == gen, bar);
;             __builtin_amdgcn_fence(__ATOMIC_ACQUIRE, "agent");
;             asm volatile("s_waitcnt vmcnt(0)" ::: "memory");
;         }
.LBB0_202:
	v_readlane_b32 s4, v254, 6
	s_lshl_b32 s4, s4, 8
	v_readlane_b32 s6, v254, 4
	v_readlane_b32 s7, v254, 5
	s_add_u32 s4, s6, s4
	s_addc_u32 s5, s7, 0
	v_mov_b32_e32 v1, 0x1000
	v_mov_b32_e32 v3, 1
	global_atomic_add v3, v1, v3, s[4:5] offset:1024 sc0
	v_cvt_f32_u32_e32 v1, v2
	v_sub_u32_e32 v4, 0, v2
	v_rcp_iflag_f32_e32 v1, v1
	s_nop 0
	v_mul_f32_e32 v1, 0x4f7ffffe, v1
	v_cvt_u32_f32_e32 v1, v1
	v_mul_lo_u32 v4, v4, v1
	v_mul_hi_u32 v4, v1, v4
	v_add_u32_e32 v1, v1, v4
	s_waitcnt vmcnt(0)
	v_mul_hi_u32 v1, v3, v1
	v_mul_lo_u32 v4, v1, v2
	v_sub_u32_e32 v4, v3, v4
	v_add_u32_e32 v5, 1, v1
	v_cmp_ge_u32_e32 vcc, v4, v2
	v_add_u32_e32 v3, 1, v3
	s_nop 0
	v_cndmask_b32_e32 v1, v1, v5, vcc
	v_sub_u32_e32 v5, v4, v2
	v_cndmask_b32_e32 v4, v4, v5, vcc
	v_add_u32_e32 v5, 1, v1
	v_cmp_ge_u32_e32 vcc, v4, v2
	s_nop 1
	v_cndmask_b32_e32 v1, v1, v5, vcc
	v_mul_lo_u32 v4, v2, v1
	v_add_u32_e32 v2, v4, v2
	v_cmp_ne_u32_e32 vcc, v3, v2
	s_and_saveexec_b64 s[6:7], vcc
	s_xor_b64 s[6:7], exec, s[6:7]
	s_cbranch_execz .LBB0_216
	s_waitcnt lgkmcnt(0)
	s_add_u32 s16, s94, 0x83500
	s_addc_u32 s17, s95, 0
	v_mov_b32_e32 v0, 0
	global_load_dword v0, v0, s[16:17] sc1
	s_waitcnt vmcnt(0)
	v_cmp_eq_u32_e32 vcc, v0, v1
	s_and_saveexec_b64 s[8:9], vcc
	s_cbranch_execz .LBB0_215
	s_add_u32 s10, s94, 0x80200
	s_addc_u32 s11, s95, 0
	s_mov_b32 s12, 1
	s_mov_b64 s[18:19], 0
	v_mov_b32_e32 v0, 0
	s_branch .LBB0_206

; __device__ __forceinline__ unsigned xb_ld(unsigned* p)              { return __hip_atomic_load(p, __ATOMIC_RELAXED, __HIP_MEMORY_SCOPE_AGENT); }
; __device__ __forceinline__ unsigned xb_add(unsigned* p, unsigned v) { return __hip_atomic_fetch_add(p, v, __ATOMIC_RELAXED, __HIP_MEMORY_SCOPE_AGENT); }
; #define XB_SPIN(cond, bar) do { unsigned _sp = 0; while (cond) { __builtin_amdgcn_s_sleep(1); \
;     if ((++_sp & 255u) == 0u) { if (xb_ld(&(bar)[XB_TMO])) break; if (_sp > XB_SPIN_CAP) { atomicAdd(&(bar)[XB_TMO], 1u); break; } } } } while (0)
; __device__ __forceinline__ void xcd_barrier(const XcdBarrier& b) {
;     ...
;         const unsigned old = xb_add(&bar[XB_XSUB(b.x)], 1u);
;         const unsigned gen = old / nloc;
;         if (old + 1u == (gen + 1u) * nloc) {
;             __builtin_amdgcn_fence(__ATOMIC_RELEASE, "agent");
;             asm volatile("s_waitcnt vmcnt(0)" ::: "memory");
;             const unsigned og = xb_add(&bar[XB_TOP], 1u);
;             const unsigned tg = og / nx;
;             if (og + 1u == (tg + 1u) * nx) xb_add(&bar[XB_TOPGEN], 1u);
;             else XB_SPIN(xb_ld(&bar[XB_TOPGEN]) == tg, bar);
;             __builtin_amdgcn_fence(__ATOMIC_ACQUIRE, "agent");
;             xb_add(&bar[XB_XGEN(b.x)], 1u);
;             asm volatile("s_waitcnt vmcnt(0)" ::: "memory");
;         } else {
;             XB_SPIN(xb_ld(&bar[XB_XGEN(b.x)]) == gen, bar);
;             __builtin_amdgcn_fence(__ATOMIC_ACQUIRE, "agent");
;             asm volatile("s_waitcnt vmcnt(0)" ::: "memory");
;         }
.LBB0_279:
	v_readlane_b32 s4, v254, 6
	s_lshl_b32 s4, s4, 8
	v_readlane_b32 s6, v254, 4
	v_readlane_b32 s7, v254, 5
	s_add_u32 s4, s6, s4
	s_addc_u32 s5, s7, 0
	v_mov_b32_e32 v1, 0x1000
	v_mov_b32_e32 v3, 1
	global_atomic_add v3, v1, v3, s[4:5] offset:1024 sc0
	v_cvt_f32_u32_e32 v1, v2
	v_sub_u32_e32 v4, 0, v2
	v_rcp_iflag_f32_e32 v1, v1
	s_nop 0
	v_mul_f32_e32 v1, 0x4f7ffffe, v1
	v_cvt_u32_f32_e32 v1, v1
	v_mul_lo_u32 v4, v4, v1
	v_mul_hi_u32 v4, v1, v4
	v_add_u32_e32 v1, v1, v4
	s_waitcnt vmcnt(0)
	v_mul_hi_u32 v1, v3, v1
	v_mul_lo_u32 v4, v1, v2
	v_sub_u32_e32 v4, v3, v4
	v_add_u32_e32 v5, 1, v1
	v_cmp_ge_u32_e32 vcc, v4, v2
	v_add_u32_e32 v3, 1, v3
	s_nop 0
	v_cndmask_b32_e32 v1, v1, v5, vcc
	v_sub_u32_e32 v5, v4, v2
	v_cndmask_b32_e32 v4, v4, v5, vcc
	v_add_u32_e32 v5, 1, v1
	v_cmp_ge_u32_e32 vcc, v4, v2
	s_nop 1
	v_cndmask_b32_e32 v1, v1, v5, vcc
	v_mul_lo_u32 v4, v2, v1
	v_add_u32_e32 v2, v4, v2
	v_cmp_ne_u32_e32 vcc, v3, v2
	s_and_saveexec_b64 s[6:7], vcc
	s_xor_b64 s[6:7], exec, s[6:7]
	s_cbranch_execz .LBB0_293
	s_waitcnt lgkmcnt(0)
	s_add_u32 s16, s94, 0x83500
	s_addc_u32 s17, s95, 0
	v_mov_b32_e32 v0, 0
	global_load_dword v0, v0, s[16:17] sc1
	s_waitcnt vmcnt(0)
	v_cmp_eq_u32_e32 vcc, v0, v1
	s_and_saveexec_b64 s[8:9], vcc
	s_cbranch_execz .LBB0_292
	s_add_u32 s10, s94, 0x80200
	s_addc_u32 s11, s95, 0
	s_mov_b32 s12, 1
	s_mov_b64 s[20:21], 0
	v_mov_b32_e32 v0, 0
	s_branch .LBB0_283

; __device__ __forceinline__ unsigned xb_ld(unsigned* p)              { return __hip_atomic_load(p, __ATOMIC_RELAXED, __HIP_MEMORY_SCOPE_AGENT); }
; __device__ __forceinline__ unsigned xb_add(unsigned* p, unsigned v) { return __hip_atomic_fetch_add(p, v, __ATOMIC_RELAXED, __HIP_MEMORY_SCOPE_AGENT); }
; #define XB_SPIN(cond, bar) do { unsigned _sp = 0; while (cond) { __builtin_amdgcn_s_sleep(1); \
;     if ((++_sp & 255u) == 0u) { if (xb_ld(&(bar)[XB_TMO])) break; if (_sp > XB_SPIN_CAP) { atomicAdd(&(bar)[XB_TMO], 1u); break; } } } } while (0)
; __device__ __forceinline__ void xcd_barrier(const XcdBarrier& b) {
;     ...
;         const unsigned old = xb_add(&bar[XB_XSUB(b.x)], 1u);
;         const unsigned gen = old / nloc;
;         if (old + 1u == (gen + 1u) * nloc) {
;             __builtin_amdgcn_fence(__ATOMIC_RELEASE, "agent");
;             asm volatile("s_waitcnt vmcnt(0)" ::: "memory");
;             const unsigned og = xb_add(&bar[XB_TOP], 1u);
;             const unsigned tg = og / nx;
;             if (og + 1u == (tg + 1u) * nx) xb_add(&bar[XB_TOPGEN], 1u);
;             else XB_SPIN(xb_ld(&bar[XB_TOPGEN]) == tg, bar);
;             __builtin_amdgcn_fence(__ATOMIC_ACQUIRE, "agent");
;             xb_add(&bar[XB_XGEN(b.x)], 1u);
;             asm volatile("s_waitcnt vmcnt(0)" ::: "memory");
;         } else {
;             XB_SPIN(xb_ld(&bar[XB_XGEN(b.x)]) == gen, bar);
;             __builtin_amdgcn_fence(__ATOMIC_ACQUIRE, "agent");
;             asm volatile("s_waitcnt vmcnt(0)" ::: "memory");
;         }
.LBB0_374:
	v_readlane_b32 s4, v254, 6
	s_lshl_b32 s4, s4, 8
	v_readlane_b32 s6, v254, 4
	v_readlane_b32 s7, v254, 5
	s_add_u32 s4, s6, s4
	s_addc_u32 s5, s7, 0
	v_mov_b32_e32 v1, 0x1000
	v_mov_b32_e32 v3, 1
	global_atomic_add v3, v1, v3, s[4:5] offset:1024 sc0
	v_cvt_f32_u32_e32 v1, v2
	v_sub_u32_e32 v4, 0, v2
	v_rcp_iflag_f32_e32 v1, v1
	s_nop 0
	v_mul_f32_e32 v1, 0x4f7ffffe, v1
	v_cvt_u32_f32_e32 v1, v1
	v_mul_lo_u32 v4, v4, v1
	v_mul_hi_u32 v4, v1, v4
	v_add_u32_e32 v1, v1, v4
	s_waitcnt vmcnt(0)
	v_mul_hi_u32 v1, v3, v1
	v_mul_lo_u32 v4, v1, v2
	v_sub_u32_e32 v4, v3, v4
	v_add_u32_e32 v5, 1, v1
	v_cmp_ge_u32_e32 vcc, v4, v2
	v_add_u32_e32 v3, 1, v3
	s_nop 0
	v_cndmask_b32_e32 v1, v1, v5, vcc
	v_sub_u32_e32 v5, v4, v2
	v_cndmask_b32_e32 v4, v4, v5, vcc
	v_add_u32_e32 v5, 1, v1
	v_cmp_ge_u32_e32 vcc, v4, v2
	s_nop 1
	v_cndmask_b32_e32 v1, v1, v5, vcc
	v_mul_lo_u32 v4, v2, v1
	v_add_u32_e32 v2, v4, v2
	v_cmp_ne_u32_e32 vcc, v3, v2
	s_and_saveexec_b64 s[6:7], vcc
	s_xor_b64 s[6:7], exec, s[6:7]
	s_cbranch_execz .LBB0_388
	s_waitcnt lgkmcnt(0)
	s_add_u32 s20, s94, 0x83500
	s_addc_u32 s21, s95, 0
	v_mov_b32_e32 v0, 0
	global_load_dword v0, v0, s[20:21] sc1
	s_waitcnt vmcnt(0)
	v_cmp_eq_u32_e32 vcc, v0, v1
	s_and_saveexec_b64 s[8:9], vcc
	s_cbranch_execz .LBB0_387
	s_add_u32 s10, s94, 0x80200
	s_addc_u32 s11, s95, 0
	s_mov_b32 s12, 1
	s_mov_b64 s[22:23], 0
	v_mov_b32_e32 v0, 0
	s_branch .LBB0_378

; __device__ __forceinline__ unsigned xb_ld(unsigned* p)              { return __hip_atomic_load(p, __ATOMIC_RELAXED, __HIP_MEMORY_SCOPE_AGENT); }
; __device__ __forceinline__ unsigned xb_add(unsigned* p, unsigned v) { return __hip_atomic_fetch_add(p, v, __ATOMIC_RELAXED, __HIP_MEMORY_SCOPE_AGENT); }
; #define XB_SPIN(cond, bar) do { unsigned _sp = 0; while (cond) { __builtin_amdgcn_s_sleep(1); \
;     if ((++_sp & 255u) == 0u) { if (xb_ld(&(bar)[XB_TMO])) break; if (_sp > XB_SPIN_CAP) { atomicAdd(&(bar)[XB_TMO], 1u); break; } } } } while (0)
; __device__ __forceinline__ void xcd_barrier(const XcdBarrier& b) {
;     ...
;         const unsigned old = xb_add(&bar[XB_XSUB(b.x)], 1u);
;         const unsigned gen = old / nloc;
;         if (old + 1u == (gen + 1u) * nloc) {
;             __builtin_amdgcn_fence(__ATOMIC_RELEASE, "agent");
;             asm volatile("s_waitcnt vmcnt(0)" ::: "memory");
;             const unsigned og = xb_add(&bar[XB_TOP], 1u);
;             const unsigned tg = og / nx;
;             if (og + 1u == (tg + 1u) * nx) xb_add(&bar[XB_TOPGEN], 1u);
;             else XB_SPIN(xb_ld(&bar[XB_TOPGEN]) == tg, bar);
;             __builtin_amdgcn_fence(__ATOMIC_ACQUIRE, "agent");
;             xb_add(&bar[XB_XGEN(b.x)], 1u);
;             asm volatile("s_waitcnt vmcnt(0)" ::: "memory");
;         } else {
;             XB_SPIN(xb_ld(&bar[XB_XGEN(b.x)]) == gen, bar);
;             __builtin_amdgcn_fence(__ATOMIC_ACQUIRE, "agent");
;             asm volatile("s_waitcnt vmcnt(0)" ::: "memory");
;         }
.LBB0_557:
	v_readlane_b32 s4, v254, 6
	s_lshl_b32 s4, s4, 8
	v_readlane_b32 s6, v254, 4
	v_readlane_b32 s7, v254, 5
	s_add_u32 s4, s6, s4
	s_addc_u32 s5, s7, 0
	v_mov_b32_e32 v1, 0x1000
	v_mov_b32_e32 v3, 1
	global_atomic_add v3, v1, v3, s[4:5] offset:1024 sc0
	v_cvt_f32_u32_e32 v1, v2
	v_sub_u32_e32 v4, 0, v2
	v_rcp_iflag_f32_e32 v1, v1
	s_nop 0
	v_mul_f32_e32 v1, 0x4f7ffffe, v1
	v_cvt_u32_f32_e32 v1, v1
	v_mul_lo_u32 v4, v4, v1
	v_mul_hi_u32 v4, v1, v4
	v_add_u32_e32 v1, v1, v4
	s_waitcnt vmcnt(0)
	v_mul_hi_u32 v1, v3, v1
	v_mul_lo_u32 v4, v1, v2
	v_sub_u32_e32 v4, v3, v4
	v_add_u32_e32 v5, 1, v1
	v_cmp_ge_u32_e32 vcc, v4, v2
	v_add_u32_e32 v3, 1, v3
	s_nop 0
	v_cndmask_b32_e32 v1, v1, v5, vcc
	v_sub_u32_e32 v5, v4, v2
	v_cndmask_b32_e32 v4, v4, v5, vcc
	v_add_u32_e32 v5, 1, v1
	v_cmp_ge_u32_e32 vcc, v4, v2
	s_nop 1
	v_cndmask_b32_e32 v1, v1, v5, vcc
	v_mul_lo_u32 v4, v2, v1
	v_add_u32_e32 v2, v4, v2
	v_cmp_ne_u32_e32 vcc, v3, v2
	s_and_saveexec_b64 s[6:7], vcc
	s_xor_b64 s[6:7], exec, s[6:7]
	s_cbranch_execz .LBB0_571
	s_waitcnt lgkmcnt(0)
	s_add_u32 s22, s94, 0x83500
	s_addc_u32 s23, s95, 0
	v_mov_b32_e32 v0, 0
	global_load_dword v0, v0, s[22:23] sc1
	s_waitcnt vmcnt(0)
	v_cmp_eq_u32_e32 vcc, v0, v1
	s_and_saveexec_b64 s[8:9], vcc
	s_cbranch_execz .LBB0_570
	s_add_u32 s10, s94, 0x80200
	s_addc_u32 s11, s95, 0
	s_mov_b32 s12, 1
	s_mov_b64 s[24:25], 0
	v_mov_b32_e32 v0, 0
	s_branch .LBB0_561

; __device__ __forceinline__ unsigned xb_ld(unsigned* p)              { return __hip_atomic_load(p, __ATOMIC_RELAXED, __HIP_MEMORY_SCOPE_AGENT); }
; __device__ __forceinline__ unsigned xb_add(unsigned* p, unsigned v) { return __hip_atomic_fetch_add(p, v, __ATOMIC_RELAXED, __HIP_MEMORY_SCOPE_AGENT); }
; #define XB_SPIN(cond, bar) do { unsigned _sp = 0; while (cond) { __builtin_amdgcn_s_sleep(1); \
;     if ((++_sp & 255u) == 0u) { if (xb_ld(&(bar)[XB_TMO])) break; if (_sp > XB_SPIN_CAP) { atomicAdd(&(bar)[XB_TMO], 1u); break; } } } } while (0)
; __device__ __forceinline__ void xcd_barrier(const XcdBarrier& b) {
;     ...
;         const unsigned old = xb_add(&bar[XB_XSUB(b.x)], 1u);
;         const unsigned gen = old / nloc;
;         if (old + 1u == (gen + 1u) * nloc) {
;             __builtin_amdgcn_fence(__ATOMIC_RELEASE, "agent");
;             asm volatile("s_waitcnt vmcnt(0)" ::: "memory");
;             const unsigned og = xb_add(&bar[XB_TOP], 1u);
;             const unsigned tg = og / nx;
;             if (og + 1u == (tg + 1u) * nx) xb_add(&bar[XB_TOPGEN], 1u);
;             else XB_SPIN(xb_ld(&bar[XB_TOPGEN]) == tg, bar);
;             __builtin_amdgcn_fence(__ATOMIC_ACQUIRE, "agent");
;             xb_add(&bar[XB_XGEN(b.x)], 1u);
;             asm volatile("s_waitcnt vmcnt(0)" ::: "memory");
;         } else {
;             XB_SPIN(xb_ld(&bar[XB_XGEN(b.x)]) == gen, bar);
;             __builtin_amdgcn_fence(__ATOMIC_ACQUIRE, "agent");
;             asm volatile("s_waitcnt vmcnt(0)" ::: "memory");
;         }
.LBB0_1313:
	v_readlane_b32 s4, v254, 6
	s_lshl_b32 s4, s4, 8
	v_readlane_b32 s6, v254, 4
	v_readlane_b32 s7, v254, 5
	s_add_u32 s4, s6, s4
	s_addc_u32 s5, s7, 0
	v_mov_b32_e32 v1, 0x1000
	v_mov_b32_e32 v3, 1
	global_atomic_add v3, v1, v3, s[4:5] offset:1024 sc0
	v_cvt_f32_u32_e32 v1, v2
	v_sub_u32_e32 v4, 0, v2
	v_rcp_iflag_f32_e32 v1, v1
	s_nop 0
	v_mul_f32_e32 v1, 0x4f7ffffe, v1
	v_cvt_u32_f32_e32 v1, v1
	v_mul_lo_u32 v4, v4, v1
	v_mul_hi_u32 v4, v1, v4
	v_add_u32_e32 v1, v1, v4
	s_waitcnt vmcnt(0)
	v_mul_hi_u32 v1, v3, v1
	v_mul_lo_u32 v4, v1, v2
	v_sub_u32_e32 v4, v3, v4
	v_add_u32_e32 v5, 1, v1
	v_cmp_ge_u32_e32 vcc, v4, v2
	v_add_u32_e32 v3, 1, v3
	s_nop 0
	v_cndmask_b32_e32 v1, v1, v5, vcc
	v_sub_u32_e32 v5, v4, v2
	v_cndmask_b32_e32 v4, v4, v5, vcc
	v_add_u32_e32 v5, 1, v1
	v_cmp_ge_u32_e32 vcc, v4, v2
	s_nop 1
	v_cndmask_b32_e32 v1, v1, v5, vcc
	v_mul_lo_u32 v4, v2, v1
	v_add_u32_e32 v2, v4, v2
	v_cmp_ne_u32_e32 vcc, v3, v2
	s_and_saveexec_b64 s[6:7], vcc
	s_xor_b64 s[6:7], exec, s[6:7]
	s_cbranch_execz .LBB0_1327
	s_waitcnt lgkmcnt(0)
	s_add_u32 s18, s94, 0x83500
	s_addc_u32 s19, s95, 0
	v_mov_b32_e32 v0, 0
	global_load_dword v0, v0, s[18:19] sc1
	s_waitcnt vmcnt(0)
	v_cmp_eq_u32_e32 vcc, v0, v1
	s_and_saveexec_b64 s[8:9], vcc
	s_cbranch_execz .LBB0_1326
	s_add_u32 s10, s94, 0x80200
	s_addc_u32 s11, s95, 0
	s_mov_b32 s12, 1
	s_mov_b64 s[22:23], 0
	v_mov_b32_e32 v0, 0
	s_branch .LBB0_1317

; __device__ __forceinline__ unsigned xb_ld(unsigned* p)              { return __hip_atomic_load(p, __ATOMIC_RELAXED, __HIP_MEMORY_SCOPE_AGENT); }
; __device__ __forceinline__ unsigned xb_add(unsigned* p, unsigned v) { return __hip_atomic_fetch_add(p, v, __ATOMIC_RELAXED, __HIP_MEMORY_SCOPE_AGENT); }
; #define XB_SPIN(cond, bar) do { unsigned _sp = 0; while (cond) { __builtin_amdgcn_s_sleep(1); \
;     if ((++_sp & 255u) == 0u) { if (xb_ld(&(bar)[XB_TMO])) break; if (_sp > XB_SPIN_CAP) { atomicAdd(&(bar)[XB_TMO], 1u); break; } } } } while (0)
; __device__ __forceinline__ void xcd_barrier(const XcdBarrier& b) {
;     ...
;         const unsigned old = xb_add(&bar[XB_XSUB(b.x)], 1u);
;         const unsigned gen = old / nloc;
;         if (old + 1u == (gen + 1u) * nloc) {
;             __builtin_amdgcn_fence(__ATOMIC_RELEASE, "agent");
;             asm volatile("s_waitcnt vmcnt(0)" ::: "memory");
;             const unsigned og = xb_add(&bar[XB_TOP], 1u);
;             const unsigned tg = og / nx;
;             if (og + 1u == (tg + 1u) * nx) xb_add(&bar[XB_TOPGEN], 1u);
;             else XB_SPIN(xb_ld(&bar[XB_TOPGEN]) == tg, bar);
;             __builtin_amdgcn_fence(__ATOMIC_ACQUIRE, "agent");
;             xb_add(&bar[XB_XGEN(b.x)], 1u);
;             asm volatile("s_waitcnt vmcnt(0)" ::: "memory");
;         } else {
;             XB_SPIN(xb_ld(&bar[XB_XGEN(b.x)]) == gen, bar);
;             __builtin_amdgcn_fence(__ATOMIC_ACQUIRE, "agent");
;             asm volatile("s_waitcnt vmcnt(0)" ::: "memory");
;         }
.LBB0_1461:
	v_readlane_b32 s2, v254, 6
	s_lshl_b32 s2, s2, 8
	v_readlane_b32 s4, v254, 4
	v_readlane_b32 s5, v254, 5
	s_add_u32 s2, s4, s2
	s_addc_u32 s3, s5, 0
	v_mov_b32_e32 v1, 0x1000
	v_mov_b32_e32 v3, 1
	global_atomic_add v3, v1, v3, s[2:3] offset:1024 sc0
	v_cvt_f32_u32_e32 v1, v2
	v_sub_u32_e32 v4, 0, v2
	v_rcp_iflag_f32_e32 v1, v1
	s_nop 0
	v_mul_f32_e32 v1, 0x4f7ffffe, v1
	v_cvt_u32_f32_e32 v1, v1
	v_mul_lo_u32 v4, v4, v1
	v_mul_hi_u32 v4, v1, v4
	v_add_u32_e32 v1, v1, v4
	s_waitcnt vmcnt(0)
	v_mul_hi_u32 v1, v3, v1
	v_mul_lo_u32 v4, v1, v2
	v_sub_u32_e32 v4, v3, v4
	v_add_u32_e32 v5, 1, v1
	v_cmp_ge_u32_e32 vcc, v4, v2
	v_add_u32_e32 v3, 1, v3
	s_nop 0
	v_cndmask_b32_e32 v1, v1, v5, vcc
	v_sub_u32_e32 v5, v4, v2
	v_cndmask_b32_e32 v4, v4, v5, vcc
	v_add_u32_e32 v5, 1, v1
	v_cmp_ge_u32_e32 vcc, v4, v2
	s_nop 1
	v_cndmask_b32_e32 v1, v1, v5, vcc
	v_mul_lo_u32 v4, v2, v1
	v_add_u32_e32 v2, v4, v2
	v_cmp_ne_u32_e32 vcc, v3, v2
	s_and_saveexec_b64 s[4:5], vcc
	s_xor_b64 s[4:5], exec, s[4:5]
	s_cbranch_execz .LBB0_1475
	s_waitcnt lgkmcnt(0)
	s_add_u32 s10, s94, 0x83500
	s_addc_u32 s11, s95, 0
	v_mov_b32_e32 v0, 0
	global_load_dword v0, v0, s[10:11] sc1
	s_waitcnt vmcnt(0)
	v_cmp_eq_u32_e32 vcc, v0, v1
	s_and_saveexec_b64 s[6:7], vcc
	s_cbranch_execz .LBB0_1474
	s_add_u32 s8, s94, 0x80200
	s_addc_u32 s9, s95, 0
	s_mov_b32 s12, 1
	s_mov_b64 s[14:15], 0
	v_mov_b32_e32 v0, 0
	s_branch .LBB0_1465
